# attention: first-half global loads spread earlier across the cvt tail (one before the last QK MFMA)
# baseline (speedup 1.0000x reference)
; #define SBAR() __builtin_amdgcn_sched_barrier(0)
; __device__ __forceinline__ void finishSM(f32x16& p0, f32x16& p1, float alpha, float& l_reg, bf16x8& pa0, bf16x8& pa1, bf16x8& pa2, bf16x8& pa3) {
;   for (int r = 0; r < 16; ++r) p1[r] = __builtin_amdgcn_exp2f(p1[r]);
;   float ps = 0; for (int r = 0; r < 16; ++r) ps += p0[r]; for (int r = 0; r < 16; ++r) ps += p1[r];
;   { auto rr = __builtin_amdgcn_permlane32_swap(__float_as_uint(ps), __float_as_uint(ps), false, false);
;     ps = __uint_as_float(rr[0]) + __uint_as_float(rr[1]); }
;   l_reg = l_reg * alpha + ps;
;     ...
;   PK4(p0, 0, pa0); PK4(p0, 8, pa1); PK4(p1, 0, pa2); PK4(p1, 8, pa3);
; template <typename TQ>
; __device__ __forceinline__ void attn_dense_body(const TQ* __restrict__ Qb, const bf16* __restrict__ Kh, const bf16* __restrict__ Vh,
;                                                 unsigned short* __restrict__ Ob, int seq, char* lds, const int wave_s) {
;     ...
;     SBAR(); qkt(pB0, pB1, (bf16*)((char*)K_lds + SHM_K), qr, r32, hi);
;     finishSM(pA0, pA1, alA, l_reg, pa0, pa1, pa2, pa3); SBAR();
.LBB0_575:
	ds_read_b128 v[64:67], v189 offset:49152
	ds_read_b128 v[68:71], v189 offset:57344
	ds_read_b128 v[210:213], v199 offset:49152
	ds_read_b128 v[214:217], v199 offset:57344
	ds_read_b128 v[240:243], v192 offset:49152
	ds_read_b128 v[244:247], v192 offset:57344
	v_add_f32_e32 v160, v175, v161
	s_waitcnt lgkmcnt(5)
	v_mfma_f32_32x32x16_bf16 v[80:95], v[64:67], v[112:115], 0
	v_add_f32_e32 v160, v162, v160
	v_add_f32_e32 v160, v206, v160
	v_add_f32_e32 v160, v174, v160
	v_add_f32_e32 v160, v209, v160
	v_add_f32_e32 v160, v163, v160
	v_add_f32_e32 v160, v173, v160
	v_add_f32_e32 v160, v169, v160
	s_waitcnt lgkmcnt(4)
	v_mfma_f32_32x32x16_bf16 v[64:79], v[68:71], v[112:115], 0
	v_add_f32_e32 v160, v171, v160
	v_add_f32_e32 v160, v170, v160
	v_add_f32_e32 v160, v172, v160
	v_exp_f32_e32 v158, v158
	v_add_f32_e32 v160, v165, v160
	v_exp_f32_e32 v159, v159
	v_add_f32_e32 v160, v167, v160
	s_waitcnt lgkmcnt(3)
	v_mfma_f32_32x32x16_bf16 v[80:95], v[210:213], v[108:111], v[80:95]
	v_exp_f32_e32 v156, v156
	v_add_f32_e32 v160, v166, v160
	v_exp_f32_e32 v157, v157
	v_add_f32_e32 v160, v168, v160
	v_exp_f32_e32 v152, v152
	v_add_f32_e32 v160, v158, v160
	v_exp_f32_e32 v153, v153
	s_waitcnt lgkmcnt(2)
	v_mfma_f32_32x32x16_bf16 v[64:79], v[214:217], v[108:111], v[64:79]
	ds_read_b128 v[210:213], v191 offset:49152
	ds_read_b128 v[214:217], v191 offset:57344
	v_add_f32_e32 v160, v159, v160
	v_exp_f32_e32 v148, v148
	v_add_f32_e32 v160, v156, v160
	v_exp_f32_e32 v149, v149
	v_add_f32_e32 v160, v157, v160
	v_exp_f32_e32 v146, v146
	s_waitcnt lgkmcnt(3)
	v_mfma_f32_32x32x16_bf16 v[80:95], v[240:243], v[120:123], v[80:95]
	v_add_f32_e32 v160, v152, v160
	v_exp_f32_e32 v147, v147
	v_add_f32_e32 v160, v153, v160
	v_exp_f32_e32 v154, v154
	v_add_f32_e32 v160, v148, v160
	v_exp_f32_e32 v155, v155
	v_add_f32_e32 v160, v149, v160
	s_waitcnt lgkmcnt(2)
	v_mfma_f32_32x32x16_bf16 v[64:79], v[244:247], v[120:123], v[64:79]
	ds_read_b128 v[240:243], v189 offset:49280
	ds_read_b128 v[244:247], v189 offset:57472
	v_exp_f32_e32 v150, v150
	v_add_f32_e32 v160, v146, v160
	v_exp_f32_e32 v151, v151
	v_add_f32_e32 v160, v147, v160
	v_exp_f32_e32 v144, v144
	v_add_f32_e32 v160, v154, v160
	s_waitcnt lgkmcnt(3)
	v_mfma_f32_32x32x16_bf16 v[80:95], v[210:213], v[124:127], v[80:95]
	v_exp_f32_e32 v145, v145
	v_add_f32_e32 v160, v155, v160
	v_add_f32_e32 v160, v150, v160
	v_add_f32_e32 v160, v151, v160
	v_add_f32_e32 v160, v144, v160
	v_add_f32_e32 v203, v145, v160
	s_waitcnt lgkmcnt(2)
	v_mfma_f32_32x32x16_bf16 v[64:79], v[214:217], v[124:127], v[64:79]
	ds_read_b128 v[210:213], v199 offset:49280
	ds_read_b128 v[214:217], v199 offset:57472
	s_waitcnt lgkmcnt(3)
	v_mfma_f32_32x32x16_bf16 v[80:95], v[240:243], v[116:119], v[80:95]
	s_waitcnt lgkmcnt(2)
	v_mfma_f32_32x32x16_bf16 v[64:79], v[244:247], v[116:119], v[64:79]
	ds_read_b128 v[240:243], v192 offset:49280
	ds_read_b128 v[244:247], v192 offset:57472
	s_waitcnt lgkmcnt(3)
	v_mfma_f32_32x32x16_bf16 v[80:95], v[210:213], v[104:107], v[80:95]
	s_waitcnt lgkmcnt(2)
	v_mfma_f32_32x32x16_bf16 v[64:79], v[214:217], v[104:107], v[64:79]
	ds_read_b128 v[210:213], v191 offset:49280
	ds_read_b128 v[214:217], v191 offset:57472
	s_waitcnt lgkmcnt(3)
	v_mfma_f32_32x32x16_bf16 v[80:95], v[240:243], v[100:103], v[80:95]
	s_waitcnt lgkmcnt(2)
	v_mfma_f32_32x32x16_bf16 v[64:79], v[244:247], v[100:103], v[64:79]
	v_cvt_pk_bf16_f32 v160, v161, v175
	v_cvt_pk_bf16_f32 v161, v162, v206
	v_cvt_pk_bf16_f32 v162, v174, v209
	v_cvt_pk_bf16_f32 v163, v163, v173
	v_cvt_pk_bf16_f32 v206, v169, v171
	v_cvt_pk_bf16_f32 v207, v170, v172
	s_waitcnt lgkmcnt(1)
	v_mfma_f32_32x32x16_bf16 v[80:95], v[210:213], v[96:99], v[80:95]
	v_cvt_pk_bf16_f32 v208, v165, v167
	v_cvt_pk_bf16_f32 v209, v166, v168
	v_cvt_pk_bf16_f32 v166, v158, v159
	v_cvt_pk_bf16_f32 v167, v156, v157
	s_add_u32 s40, s52, 0x18000
	s_addc_u32 s41, s53, 0
	global_load_dwordx4 v[156:159], v176, s[40:41]
	v_cvt_pk_bf16_f32 v168, v152, v153
	s_waitcnt lgkmcnt(0)
; #define SBAR() __builtin_amdgcn_sched_barrier(0)
; #define SLOAD(i, k0) do { sr_[i].vs0 = St::ld8(&Vh[(long)((k0) + sr) * LDK + sc]); sr_[i].vs1 = St::ld8(&Vh[(long)((k0) + 32 + sr) * LDK + sc]); \
;     sr_[i].ks0 = St::ld8(&Kh[(long)((k0) + sr) * LDK + sc]); sr_[i].ks1 = St::ld8(&Kh[(long)((k0) + 32 + sr) * LDK + sc]); } while (0)
; #define SWAIT() do { if constexpr (SDEPTH == 2) asm volatile("s_waitcnt vmcnt(4)" ::: "memory"); else asm volatile("s_waitcnt vmcnt(0)" ::: "memory"); } while (0)
; template <int D0> __device__ __forceinline__ void pv_one(f32x16& od, int vb, bf16x8 pa0, bf16x8 pa1, bf16x8 pa2, bf16x8 pa3) {
;   const s16x4 l0 = tr_read<v_rd_off(D0, 0, 0)>(vb), h0 = tr_read<v_rd_off(D0, 0, 1)>(vb), l1 = tr_read<v_rd_off(D0, 1, 0)>(vb), h1 = tr_read<v_rd_off(D0, 1, 1)>(vb);
;   const s16x4 l2 = tr_read<v_rd_off(D0, 2, 0)>(vb), h2 = tr_read<v_rd_off(D0, 2, 1)>(vb), l3 = tr_read<v_rd_off(D0, 3, 0)>(vb), h3 = tr_read<v_rd_off(D0, 3, 1)>(vb);
;   asm volatile("s_waitcnt lgkmcnt(0)" ::: "memory"); SBAR();
;     ...
;   od = __builtin_amdgcn_mfma_f32_32x32x16_bf16(pa0, PK(l0, h0), od, 0, 0, 0);
;   od = __builtin_amdgcn_mfma_f32_32x32x16_bf16(pa1, PK(l1, h1), od, 0, 0, 0);
;   od = __builtin_amdgcn_mfma_f32_32x32x16_bf16(pa2, PK(l2, h2), od, 0, 0, 0);
;   od = __builtin_amdgcn_mfma_f32_32x32x16_bf16(pa3, PK(l3, h3), od, 0, 0, 0);
;     ...
; }
; __device__ __forceinline__ void pv_d0(f32x16* o, int vb, bf16x8 pa0, bf16x8 pa1, bf16x8 pa2, bf16x8 pa3) {
;   pv_one<0>(o[0], vb, pa0, pa1, pa2, pa3); pv_one<1>(o[1], vb, pa0, pa1, pa2, pa3); pv_one<2>(o[2], vb, pa0, pa1, pa2, pa3); pv_one<3>(o[3], vb, pa0, pa1, pa2, pa3);
; template <typename TQ>
; __device__ __forceinline__ void attn_dense_body(const TQ* __restrict__ Qb, const bf16* __restrict__ Kh, const bf16* __restrict__ Vh,
;                                                 unsigned short* __restrict__ Ob, int seq, char* lds, const int wave_s) {
;     ...
;     SLOAD(SO, (j + SDEPTH) * KVBLK); SBAR();
;     pv_d0(o, vb0, pa0, pa1, pa2, pa3); partialSM(pB0, pB1, m_reg, mnB, alB);
;     __syncthreads(); SWAIT(); SWRITE(0, SE);
	v_mfma_f32_32x32x16_bf16 v[64:79], v[214:217], v[96:99], v[64:79]
	v_cvt_pk_bf16_f32 v171, v154, v155
	global_load_dwordx4 v[152:155], v176, s[40:41] offset:-512
	v_cvt_pk_bf16_f32 v169, v148, v149
	v_cvt_pk_bf16_f32 v172, v150, v151
	global_load_dwordx4 v[148:151], v176, s[52:53] offset:-512
	v_cvt_pk_bf16_f32 v170, v146, v147
	v_cvt_pk_bf16_f32 v173, v144, v145
	global_load_dwordx4 v[144:147], v176, s[52:53]
	s_add_u32 s52, s52, 0x30000
	s_addc_u32 s53, s53, 0
	ds_read_b64_tr_b16 v[210:211], v184 offset:0
	ds_read_b64_tr_b16 v[212:213], v184 offset:0x800
	ds_read_b64_tr_b16 v[214:215], v184 offset:0x1000
	ds_read_b64_tr_b16 v[216:217], v184 offset:0x1800
	ds_read_b64_tr_b16 v[224:225], v184 offset:0x2000
	ds_read_b64_tr_b16 v[226:227], v184 offset:0x2800
	ds_read_b64_tr_b16 v[228:229], v184 offset:0x3000
	ds_read_b64_tr_b16 v[230:231], v184 offset:0x3800
	s_waitcnt lgkmcnt(0)
	v_mfma_f32_32x32x16_bf16 v[0:15], v[160:163], v[210:213], v[0:15]
	ds_read_b64_tr_b16 v[210:211], v184 offset:0x200
	ds_read_b64_tr_b16 v[212:213], v184 offset:0xa00
	v_mfma_f32_32x32x16_bf16 v[0:15], v[206:209], v[214:217], v[0:15]
	ds_read_b64_tr_b16 v[214:215], v184 offset:0x1200
	ds_read_b64_tr_b16 v[216:217], v184 offset:0x1a00
	v_mfma_f32_32x32x16_bf16 v[0:15], v[166:169], v[224:227], v[0:15]
	ds_read_b64_tr_b16 v[224:225], v184 offset:0x2200
	ds_read_b64_tr_b16 v[226:227], v184 offset:0x2a00
	v_mfma_f32_32x32x16_bf16 v[0:15], v[170:173], v[228:231], v[0:15]
	ds_read_b64_tr_b16 v[228:229], v184 offset:0x3200
	ds_read_b64_tr_b16 v[230:231], v184 offset:0x3a00
	s_waitcnt lgkmcnt(0)
	v_mfma_f32_32x32x16_bf16 v[48:63], v[160:163], v[210:213], v[48:63]
	ds_read_b64_tr_b16 v[210:211], v184 offset:0x400
	ds_read_b64_tr_b16 v[212:213], v184 offset:0xc00
	v_mfma_f32_32x32x16_bf16 v[48:63], v[206:209], v[214:217], v[48:63]
	ds_read_b64_tr_b16 v[214:215], v184 offset:0x1400
	ds_read_b64_tr_b16 v[216:217], v184 offset:0x1c00
	v_mfma_f32_32x32x16_bf16 v[48:63], v[166:169], v[224:227], v[48:63]
	ds_read_b64_tr_b16 v[224:225], v184 offset:0x2400
	ds_read_b64_tr_b16 v[226:227], v184 offset:0x2c00
	v_mfma_f32_32x32x16_bf16 v[48:63], v[170:173], v[228:231], v[48:63]
	ds_read_b64_tr_b16 v[228:229], v184 offset:0x3400
	ds_read_b64_tr_b16 v[230:231], v184 offset:0x3c00
	s_waitcnt lgkmcnt(0)
	v_mfma_f32_32x32x16_bf16 v[32:47], v[160:163], v[210:213], v[32:47]
	ds_read_b64_tr_b16 v[210:211], v184 offset:0x600
	ds_read_b64_tr_b16 v[212:213], v184 offset:0xe00
	v_mfma_f32_32x32x16_bf16 v[32:47], v[206:209], v[214:217], v[32:47]
	ds_read_b64_tr_b16 v[214:215], v184 offset:0x1600
	ds_read_b64_tr_b16 v[216:217], v184 offset:0x1e00
	v_mfma_f32_32x32x16_bf16 v[32:47], v[166:169], v[224:227], v[32:47]
	ds_read_b64_tr_b16 v[224:225], v184 offset:0x2600
	ds_read_b64_tr_b16 v[226:227], v184 offset:0x2e00
	v_mfma_f32_32x32x16_bf16 v[32:47], v[170:173], v[228:231], v[32:47]
	ds_read_b64_tr_b16 v[228:229], v184 offset:0x3600
	ds_read_b64_tr_b16 v[230:231], v184 offset:0x3e00
	s_waitcnt lgkmcnt(0)
	v_mfma_f32_32x32x16_bf16 v[16:31], v[160:163], v[210:213], v[16:31]
	v_max_f32_e32 v160, v80, v81
	v_max3_f32 v160, v160, v82, v83
	v_max3_f32 v160, v160, v84, v85
	v_max3_f32 v160, v160, v86, v87
	v_max3_f32 v160, v160, v88, v89
	v_max3_f32 v160, v160, v90, v91
	v_max3_f32 v160, v160, v92, v93
	v_mfma_f32_32x32x16_bf16 v[16:31], v[206:209], v[214:217], v[16:31]
	v_max3_f32 v160, v160, v94, v95
	v_max3_f32 v160, v160, v64, v65
	v_max3_f32 v160, v160, v66, v67
	v_max3_f32 v160, v160, v68, v69
	v_max3_f32 v160, v160, v70, v71
	v_max3_f32 v160, v160, v72, v73
	v_max3_f32 v160, v160, v74, v75
	v_max3_f32 v160, v160, v76, v77
	v_mfma_f32_32x32x16_bf16 v[16:31], v[166:169], v[224:227], v[16:31]
	v_max3_f32 v160, v160, v78, v79
	v_mov_b32_e32 v161, v160
	s_nop 1
	v_permlane32_swap_b32_e32 v160, v161
	v_max_f32_e32 v160, v160, v161
	v_sub_f32_e32 v161, v160, v164
	v_cmp_ge_f32_e32 vcc, s9, v161
	v_mfma_f32_32x32x16_bf16 v[16:31], v[170:173], v[228:231], v[16:31]
	s_cmp_eq_u64 vcc, exec
	s_cbranch_scc0 .Lattn_slow_a
	v_mov_b32_e32 v205, 1.0
	v_mov_b32_e32 v206, v164
	s_waitcnt vmcnt(4)
	ds_write_b128 v187, v[128:131]
	ds_write_b128 v187, v[136:139] offset:8192
	ds_write_b128 v185, v[132:135] offset:32768
	ds_write_b128 v185, v[140:143] offset:40960
